# raise MFMA-phase priority before the first LDS fragment reads of each GEMM K-step
# baseline (speedup 1.0000x reference)
.Lg1_head:
	s_cmpk_gt_u32 s27, 0x7bf
	s_waitcnt vmcnt(0)
	ds_write_b128 v205, v[134:137]
	ds_write_b128 v205, v[130:133] offset:4096
	ds_write_b128 v205, v[142:145] offset:8192
	ds_write_b128 v205, v[138:141] offset:12288
	ds_write_b128 v205, v[146:149] offset:16384
	ds_write_b128 v205, v[150:153] offset:20480
	ds_write_b128 v205, v[154:157] offset:24576
	ds_write_b128 v205, v[158:161] offset:28672
	ds_write_b128 v205, v[162:165] offset:32768
	ds_write_b128 v205, v[166:169] offset:36864
	ds_write_b128 v205, v[170:173] offset:40960
	ds_write_b128 v205, v[174:177] offset:45056
	s_waitcnt lgkmcnt(0)
	s_barrier
	s_cbranch_scc1 .Lg1_final
	s_add_i32 s27, s27, 64
	s_setprio 1
	ds_read_b128 v[178:181], v207
	ds_read_b128 v[182:185], v207 offset:4096
	ds_read_b128 v[194:197], v236 offset:16384
	ds_read_b128 v[198:201], v236 offset:20480
	ds_read_b128 v[228:231], v236 offset:24576
	s_waitcnt lgkmcnt(2)
	v_mfma_f32_32x32x16_bf16 v[114:129], v[178:181], v[194:197], v[114:129]
	v_mfma_f32_32x32x16_bf16 v[50:65], v[182:185], v[194:197], v[50:65]
	ds_read_b128 v[194:197], v236 offset:28672
	ds_read_b128 v[186:189], v223
	s_and_b64 exec, vcc, s[4:5]
	global_load_dwordx4 v[134:137], v202, s[28:29]
	s_mov_b64 exec, vcc
	s_waitcnt lgkmcnt(3)
	v_mfma_f32_32x32x16_bf16 v[98:113], v[178:181], v[198:201], v[98:113]
	v_mfma_f32_32x32x16_bf16 v[34:49], v[182:185], v[198:201], v[34:49]
	ds_read_b128 v[198:201], v237 offset:16384
	ds_read_b128 v[190:193], v223 offset:4096
	s_and_b64 exec, vcc, s[6:7]
	global_load_dwordx4 v[130:133], v203, s[28:29]
	s_mov_b64 exec, vcc
	s_waitcnt lgkmcnt(4)
	v_mfma_f32_32x32x16_bf16 v[82:97], v[178:181], v[228:231], v[82:97]
	v_mfma_f32_32x32x16_bf16 v[18:33], v[182:185], v[228:231], v[18:33]
	ds_read_b128 v[228:231], v237 offset:20480
	s_and_b64 exec, vcc, s[8:9]
	global_load_dwordx4 v[142:145], v210, s[28:29]
	s_mov_b64 exec, vcc
	s_waitcnt lgkmcnt(4)
	v_mfma_f32_32x32x16_bf16 v[66:81], v[178:181], v[194:197], v[66:81]
	v_mfma_f32_32x32x16_bf16 v[2:17], v[182:185], v[194:197], v[2:17]
	ds_read_b128 v[194:197], v237 offset:24576
	s_and_b64 exec, vcc, s[10:11]
	global_load_dwordx4 v[138:141], v232, s[28:29]
	s_mov_b64 exec, vcc
	s_add_u32 s28, s28, 0x80
	s_addc_u32 s29, s29, 0
	s_waitcnt lgkmcnt(2)
	v_mfma_f32_32x32x16_bf16 v[114:129], v[186:189], v[198:201], v[114:129]
	v_mfma_f32_32x32x16_bf16 v[50:65], v[190:193], v[198:201], v[50:65]
	ds_read_b128 v[198:201], v237 offset:28672
	ds_read_b128 v[178:181], v225
	global_load_dwordx4 v[146:149], v233, s[100:101]
	s_waitcnt lgkmcnt(3)
	v_mfma_f32_32x32x16_bf16 v[98:113], v[186:189], v[228:231], v[98:113]
	v_mfma_f32_32x32x16_bf16 v[34:49], v[190:193], v[228:231], v[34:49]
	ds_read_b128 v[228:231], v238 offset:16384
	ds_read_b128 v[182:185], v225 offset:4096
	v_add_u32_e32 v234, 0x20000, v233
	global_load_dwordx4 v[150:153], v234, s[100:101]
	s_waitcnt lgkmcnt(4)
	v_mfma_f32_32x32x16_bf16 v[82:97], v[186:189], v[194:197], v[82:97]
	v_mfma_f32_32x32x16_bf16 v[18:33], v[190:193], v[194:197], v[18:33]
	ds_read_b128 v[194:197], v238 offset:20480
	v_add_u32_e32 v235, 0x40000, v233
	global_load_dwordx4 v[154:157], v235, s[100:101]
	s_waitcnt lgkmcnt(4)
	v_mfma_f32_32x32x16_bf16 v[66:81], v[186:189], v[198:201], v[66:81]
	v_mfma_f32_32x32x16_bf16 v[2:17], v[190:193], v[198:201], v[2:17]
	ds_read_b128 v[198:201], v238 offset:24576
	v_add_u32_e32 v234, 0x60000, v233
	global_load_dwordx4 v[158:161], v234, s[100:101]
	s_waitcnt lgkmcnt(2)
	v_mfma_f32_32x32x16_bf16 v[114:129], v[178:181], v[228:231], v[114:129]
	v_mfma_f32_32x32x16_bf16 v[50:65], v[182:185], v[228:231], v[50:65]
	ds_read_b128 v[228:231], v238 offset:28672
	ds_read_b128 v[186:189], v226
	v_add_u32_e32 v235, 0x80000, v233
	global_load_dwordx4 v[162:165], v235, s[100:101]
	s_waitcnt lgkmcnt(3)
	v_mfma_f32_32x32x16_bf16 v[98:113], v[178:181], v[194:197], v[98:113]
	v_mfma_f32_32x32x16_bf16 v[34:49], v[182:185], v[194:197], v[34:49]
	ds_read_b128 v[194:197], v239 offset:16384
	ds_read_b128 v[190:193], v226 offset:4096
	v_add_u32_e32 v234, 0xa0000, v233
	global_load_dwordx4 v[166:169], v234, s[100:101]
	s_waitcnt lgkmcnt(4)
	v_mfma_f32_32x32x16_bf16 v[82:97], v[178:181], v[198:201], v[82:97]
	v_mfma_f32_32x32x16_bf16 v[18:33], v[182:185], v[198:201], v[18:33]
	ds_read_b128 v[198:201], v239 offset:20480
	v_add_u32_e32 v235, 0xc0000, v233
	global_load_dwordx4 v[170:173], v235, s[100:101]
	s_waitcnt lgkmcnt(4)
	v_mfma_f32_32x32x16_bf16 v[66:81], v[178:181], v[228:231], v[66:81]
	v_mfma_f32_32x32x16_bf16 v[2:17], v[182:185], v[228:231], v[2:17]
	ds_read_b128 v[228:231], v239 offset:24576
	v_add_u32_e32 v234, 0xe0000, v233
	global_load_dwordx4 v[174:177], v234, s[100:101]
	s_add_u32 s100, s100, 0x80
	s_addc_u32 s101, s101, 0
	s_waitcnt lgkmcnt(2)
	v_mfma_f32_32x32x16_bf16 v[114:129], v[186:189], v[194:197], v[114:129]
	v_mfma_f32_32x32x16_bf16 v[50:65], v[190:193], v[194:197], v[50:65]
	ds_read_b128 v[194:197], v239 offset:28672
	s_waitcnt lgkmcnt(2)
	v_mfma_f32_32x32x16_bf16 v[98:113], v[186:189], v[198:201], v[98:113]
	v_mfma_f32_32x32x16_bf16 v[34:49], v[190:193], v[198:201], v[34:49]
	s_waitcnt lgkmcnt(1)
	v_mfma_f32_32x32x16_bf16 v[82:97], v[186:189], v[228:231], v[82:97]
	v_mfma_f32_32x32x16_bf16 v[18:33], v[190:193], v[228:231], v[18:33]
	s_waitcnt lgkmcnt(0)
	v_mfma_f32_32x32x16_bf16 v[66:81], v[186:189], v[194:197], v[66:81]
	v_mfma_f32_32x32x16_bf16 v[2:17], v[190:193], v[194:197], v[2:17]
	s_setprio 0
	s_barrier
	s_branch .Lg1_head
.Lg1_final:
	s_add_i32 s27, s27, 64
	s_setprio 1
	ds_read_b128 v[178:181], v207
	ds_read_b128 v[182:185], v207 offset:4096
	ds_read_b128 v[194:197], v236 offset:16384
	ds_read_b128 v[198:201], v236 offset:20480
	ds_read_b128 v[228:231], v236 offset:24576
	s_waitcnt lgkmcnt(2)
	v_mfma_f32_32x32x16_bf16 v[114:129], v[178:181], v[194:197], v[114:129]
	v_mfma_f32_32x32x16_bf16 v[50:65], v[182:185], v[194:197], v[50:65]
	ds_read_b128 v[194:197], v236 offset:28672
	ds_read_b128 v[186:189], v223
	s_waitcnt lgkmcnt(3)
	v_mfma_f32_32x32x16_bf16 v[98:113], v[178:181], v[198:201], v[98:113]
	v_mfma_f32_32x32x16_bf16 v[34:49], v[182:185], v[198:201], v[34:49]
	ds_read_b128 v[198:201], v237 offset:16384
	ds_read_b128 v[190:193], v223 offset:4096
	s_waitcnt lgkmcnt(4)
	v_mfma_f32_32x32x16_bf16 v[82:97], v[178:181], v[228:231], v[82:97]
	v_mfma_f32_32x32x16_bf16 v[18:33], v[182:185], v[228:231], v[18:33]
	ds_read_b128 v[228:231], v237 offset:20480
	s_waitcnt lgkmcnt(4)
	v_mfma_f32_32x32x16_bf16 v[66:81], v[178:181], v[194:197], v[66:81]
	v_mfma_f32_32x32x16_bf16 v[2:17], v[182:185], v[194:197], v[2:17]
	ds_read_b128 v[194:197], v237 offset:24576
	s_waitcnt lgkmcnt(2)
	v_mfma_f32_32x32x16_bf16 v[114:129], v[186:189], v[198:201], v[114:129]
	v_mfma_f32_32x32x16_bf16 v[50:65], v[190:193], v[198:201], v[50:65]
	ds_read_b128 v[198:201], v237 offset:28672
	ds_read_b128 v[178:181], v225
	s_waitcnt lgkmcnt(3)
	v_mfma_f32_32x32x16_bf16 v[98:113], v[186:189], v[228:231], v[98:113]
	v_mfma_f32_32x32x16_bf16 v[34:49], v[190:193], v[228:231], v[34:49]
	ds_read_b128 v[228:231], v238 offset:16384
	ds_read_b128 v[182:185], v225 offset:4096
	s_waitcnt lgkmcnt(4)
	v_mfma_f32_32x32x16_bf16 v[82:97], v[186:189], v[194:197], v[82:97]
	v_mfma_f32_32x32x16_bf16 v[18:33], v[190:193], v[194:197], v[18:33]
	ds_read_b128 v[194:197], v238 offset:20480
	s_waitcnt lgkmcnt(4)
	v_mfma_f32_32x32x16_bf16 v[66:81], v[186:189], v[198:201], v[66:81]
	v_mfma_f32_32x32x16_bf16 v[2:17], v[190:193], v[198:201], v[2:17]
	ds_read_b128 v[198:201], v238 offset:24576
	s_waitcnt lgkmcnt(2)
	v_mfma_f32_32x32x16_bf16 v[114:129], v[178:181], v[228:231], v[114:129]
	v_mfma_f32_32x32x16_bf16 v[50:65], v[182:185], v[228:231], v[50:65]
	ds_read_b128 v[228:231], v238 offset:28672
	ds_read_b128 v[186:189], v226
	s_waitcnt lgkmcnt(3)
	v_mfma_f32_32x32x16_bf16 v[98:113], v[178:181], v[194:197], v[98:113]
	v_mfma_f32_32x32x16_bf16 v[34:49], v[182:185], v[194:197], v[34:49]
	ds_read_b128 v[194:197], v239 offset:16384
	ds_read_b128 v[190:193], v226 offset:4096
	s_waitcnt lgkmcnt(4)
	v_mfma_f32_32x32x16_bf16 v[82:97], v[178:181], v[198:201], v[82:97]
	v_mfma_f32_32x32x16_bf16 v[18:33], v[182:185], v[198:201], v[18:33]
	ds_read_b128 v[198:201], v239 offset:20480
	s_waitcnt lgkmcnt(4)
	v_mfma_f32_32x32x16_bf16 v[66:81], v[178:181], v[228:231], v[66:81]
	v_mfma_f32_32x32x16_bf16 v[2:17], v[182:185], v[228:231], v[2:17]
	ds_read_b128 v[228:231], v239 offset:24576
	s_waitcnt lgkmcnt(2)
	v_mfma_f32_32x32x16_bf16 v[114:129], v[186:189], v[194:197], v[114:129]
	v_mfma_f32_32x32x16_bf16 v[50:65], v[190:193], v[194:197], v[50:65]
	ds_read_b128 v[194:197], v239 offset:28672
	s_waitcnt lgkmcnt(2)
	v_mfma_f32_32x32x16_bf16 v[98:113], v[186:189], v[198:201], v[98:113]
	v_mfma_f32_32x32x16_bf16 v[34:49], v[190:193], v[198:201], v[34:49]
	s_waitcnt lgkmcnt(1)
	v_mfma_f32_32x32x16_bf16 v[82:97], v[186:189], v[228:231], v[82:97]
	v_mfma_f32_32x32x16_bf16 v[18:33], v[190:193], v[228:231], v[18:33]
	s_waitcnt lgkmcnt(0)
	v_mfma_f32_32x32x16_bf16 v[66:81], v[186:189], v[194:197], v[66:81]
	v_mfma_f32_32x32x16_bf16 v[2:17], v[190:193], v[194:197], v[2:17]
	s_setprio 0
	s_barrier
	s_mov_b64 s[2:3], -1
	s_mov_b64 vcc, 0
	s_branch .LBB0_475

.Lg2_head:
	s_cmpk_gt_u32 s29, 0x7bf
	s_waitcnt vmcnt(0)
	ds_write_b128 v205, v[134:137]
	ds_write_b128 v205, v[130:133] offset:4096
	ds_write_b128 v205, v[142:145] offset:8192
	ds_write_b128 v205, v[138:141] offset:12288
	ds_write_b128 v205, v[146:149] offset:16384
	ds_write_b128 v205, v[150:153] offset:20480
	ds_write_b128 v205, v[154:157] offset:24576
	ds_write_b128 v205, v[158:161] offset:28672
	ds_write_b128 v205, v[162:165] offset:32768
	ds_write_b128 v205, v[166:169] offset:36864
	ds_write_b128 v205, v[170:173] offset:40960
	ds_write_b128 v205, v[174:177] offset:45056
	s_waitcnt lgkmcnt(0)
	s_barrier
	s_cbranch_scc1 .Lg2_final
	s_add_i32 s29, s29, 64
	s_setprio 1
	ds_read_b128 v[178:181], v207
	ds_read_b128 v[182:185], v207 offset:4096
	ds_read_b128 v[194:197], v236 offset:16384
	ds_read_b128 v[198:201], v236 offset:20480
	ds_read_b128 v[228:231], v236 offset:24576
	s_waitcnt lgkmcnt(2)
	v_mfma_f32_32x32x16_bf16 v[114:129], v[178:181], v[194:197], v[114:129]
	v_mfma_f32_32x32x16_bf16 v[50:65], v[182:185], v[194:197], v[50:65]
	ds_read_b128 v[194:197], v236 offset:28672
	ds_read_b128 v[186:189], v223
	s_and_b64 exec, vcc, s[6:7]
	global_load_dwordx4 v[134:137], v202, s[4:5]
	s_mov_b64 exec, vcc
	s_waitcnt lgkmcnt(3)
	v_mfma_f32_32x32x16_bf16 v[98:113], v[178:181], v[198:201], v[98:113]
	v_mfma_f32_32x32x16_bf16 v[34:49], v[182:185], v[198:201], v[34:49]
	ds_read_b128 v[198:201], v237 offset:16384
	ds_read_b128 v[190:193], v223 offset:4096
	s_and_b64 exec, vcc, s[8:9]
	global_load_dwordx4 v[130:133], v203, s[4:5]
	s_mov_b64 exec, vcc
	s_waitcnt lgkmcnt(4)
	v_mfma_f32_32x32x16_bf16 v[82:97], v[178:181], v[228:231], v[82:97]
	v_mfma_f32_32x32x16_bf16 v[18:33], v[182:185], v[228:231], v[18:33]
	ds_read_b128 v[228:231], v237 offset:20480
	s_and_b64 exec, vcc, s[10:11]
	global_load_dwordx4 v[142:145], v210, s[4:5]
	s_mov_b64 exec, vcc
	s_waitcnt lgkmcnt(4)
	v_mfma_f32_32x32x16_bf16 v[66:81], v[178:181], v[194:197], v[66:81]
	v_mfma_f32_32x32x16_bf16 v[2:17], v[182:185], v[194:197], v[2:17]
	ds_read_b128 v[194:197], v237 offset:24576
	s_and_b64 exec, vcc, s[12:13]
	global_load_dwordx4 v[138:141], v232, s[4:5]
	s_mov_b64 exec, vcc
	s_add_u32 s4, s4, 0x80
	s_addc_u32 s5, s5, 0
	s_waitcnt lgkmcnt(2)
	v_mfma_f32_32x32x16_bf16 v[114:129], v[186:189], v[198:201], v[114:129]
	v_mfma_f32_32x32x16_bf16 v[50:65], v[190:193], v[198:201], v[50:65]
	ds_read_b128 v[198:201], v237 offset:28672
	ds_read_b128 v[178:181], v225
	global_load_dwordx4 v[146:149], v233, s[100:101]
	s_waitcnt lgkmcnt(3)
	v_mfma_f32_32x32x16_bf16 v[98:113], v[186:189], v[228:231], v[98:113]
	v_mfma_f32_32x32x16_bf16 v[34:49], v[190:193], v[228:231], v[34:49]
	ds_read_b128 v[228:231], v238 offset:16384
	ds_read_b128 v[182:185], v225 offset:4096
	v_add_u32_e32 v234, 0x20000, v233
	global_load_dwordx4 v[150:153], v234, s[100:101]
	s_waitcnt lgkmcnt(4)
	v_mfma_f32_32x32x16_bf16 v[82:97], v[186:189], v[194:197], v[82:97]
	v_mfma_f32_32x32x16_bf16 v[18:33], v[190:193], v[194:197], v[18:33]
	ds_read_b128 v[194:197], v238 offset:20480
	v_add_u32_e32 v235, 0x40000, v233
	global_load_dwordx4 v[154:157], v235, s[100:101]
	s_waitcnt lgkmcnt(4)
	v_mfma_f32_32x32x16_bf16 v[66:81], v[186:189], v[198:201], v[66:81]
	v_mfma_f32_32x32x16_bf16 v[2:17], v[190:193], v[198:201], v[2:17]
	ds_read_b128 v[198:201], v238 offset:24576
	v_add_u32_e32 v234, 0x60000, v233
	global_load_dwordx4 v[158:161], v234, s[100:101]
	s_waitcnt lgkmcnt(2)
	v_mfma_f32_32x32x16_bf16 v[114:129], v[178:181], v[228:231], v[114:129]
	v_mfma_f32_32x32x16_bf16 v[50:65], v[182:185], v[228:231], v[50:65]
	ds_read_b128 v[228:231], v238 offset:28672
	ds_read_b128 v[186:189], v226
	v_add_u32_e32 v235, 0x80000, v233
	global_load_dwordx4 v[162:165], v235, s[100:101]
	s_waitcnt lgkmcnt(3)
	v_mfma_f32_32x32x16_bf16 v[98:113], v[178:181], v[194:197], v[98:113]
	v_mfma_f32_32x32x16_bf16 v[34:49], v[182:185], v[194:197], v[34:49]
	ds_read_b128 v[194:197], v239 offset:16384
	ds_read_b128 v[190:193], v226 offset:4096
	v_add_u32_e32 v234, 0xa0000, v233
	global_load_dwordx4 v[166:169], v234, s[100:101]
	s_waitcnt lgkmcnt(4)
	v_mfma_f32_32x32x16_bf16 v[82:97], v[178:181], v[198:201], v[82:97]
	v_mfma_f32_32x32x16_bf16 v[18:33], v[182:185], v[198:201], v[18:33]
	ds_read_b128 v[198:201], v239 offset:20480
	v_add_u32_e32 v235, 0xc0000, v233
	global_load_dwordx4 v[170:173], v235, s[100:101]
	s_waitcnt lgkmcnt(4)
	v_mfma_f32_32x32x16_bf16 v[66:81], v[178:181], v[228:231], v[66:81]
	v_mfma_f32_32x32x16_bf16 v[2:17], v[182:185], v[228:231], v[2:17]
	ds_read_b128 v[228:231], v239 offset:24576
	v_add_u32_e32 v234, 0xe0000, v233
	global_load_dwordx4 v[174:177], v234, s[100:101]
	s_add_u32 s100, s100, 0x80
	s_addc_u32 s101, s101, 0
	s_waitcnt lgkmcnt(2)
	v_mfma_f32_32x32x16_bf16 v[114:129], v[186:189], v[194:197], v[114:129]
	v_mfma_f32_32x32x16_bf16 v[50:65], v[190:193], v[194:197], v[50:65]
	ds_read_b128 v[194:197], v239 offset:28672
	s_waitcnt lgkmcnt(2)
	v_mfma_f32_32x32x16_bf16 v[98:113], v[186:189], v[198:201], v[98:113]
	v_mfma_f32_32x32x16_bf16 v[34:49], v[190:193], v[198:201], v[34:49]
	s_waitcnt lgkmcnt(1)
	v_mfma_f32_32x32x16_bf16 v[82:97], v[186:189], v[228:231], v[82:97]
	v_mfma_f32_32x32x16_bf16 v[18:33], v[190:193], v[228:231], v[18:33]
	s_waitcnt lgkmcnt(0)
	v_mfma_f32_32x32x16_bf16 v[66:81], v[186:189], v[194:197], v[66:81]
	v_mfma_f32_32x32x16_bf16 v[2:17], v[190:193], v[194:197], v[2:17]
	s_setprio 0
	s_barrier
	s_branch .Lg2_head
.Lg2_final:
	s_add_i32 s29, s29, 64
	s_setprio 1
	ds_read_b128 v[178:181], v207
	ds_read_b128 v[182:185], v207 offset:4096
	ds_read_b128 v[194:197], v236 offset:16384
	ds_read_b128 v[198:201], v236 offset:20480
	ds_read_b128 v[228:231], v236 offset:24576
	s_waitcnt lgkmcnt(2)
	v_mfma_f32_32x32x16_bf16 v[114:129], v[178:181], v[194:197], v[114:129]
	v_mfma_f32_32x32x16_bf16 v[50:65], v[182:185], v[194:197], v[50:65]
	ds_read_b128 v[194:197], v236 offset:28672
	ds_read_b128 v[186:189], v223
	s_waitcnt lgkmcnt(3)
	v_mfma_f32_32x32x16_bf16 v[98:113], v[178:181], v[198:201], v[98:113]
	v_mfma_f32_32x32x16_bf16 v[34:49], v[182:185], v[198:201], v[34:49]
	ds_read_b128 v[198:201], v237 offset:16384
	ds_read_b128 v[190:193], v223 offset:4096
	s_waitcnt lgkmcnt(4)
	v_mfma_f32_32x32x16_bf16 v[82:97], v[178:181], v[228:231], v[82:97]
	v_mfma_f32_32x32x16_bf16 v[18:33], v[182:185], v[228:231], v[18:33]
	ds_read_b128 v[228:231], v237 offset:20480
	s_waitcnt lgkmcnt(4)
	v_mfma_f32_32x32x16_bf16 v[66:81], v[178:181], v[194:197], v[66:81]
	v_mfma_f32_32x32x16_bf16 v[2:17], v[182:185], v[194:197], v[2:17]
	ds_read_b128 v[194:197], v237 offset:24576
	s_waitcnt lgkmcnt(2)
	v_mfma_f32_32x32x16_bf16 v[114:129], v[186:189], v[198:201], v[114:129]
	v_mfma_f32_32x32x16_bf16 v[50:65], v[190:193], v[198:201], v[50:65]
	ds_read_b128 v[198:201], v237 offset:28672
	ds_read_b128 v[178:181], v225
	s_waitcnt lgkmcnt(3)
	v_mfma_f32_32x32x16_bf16 v[98:113], v[186:189], v[228:231], v[98:113]
	v_mfma_f32_32x32x16_bf16 v[34:49], v[190:193], v[228:231], v[34:49]
	ds_read_b128 v[228:231], v238 offset:16384
	ds_read_b128 v[182:185], v225 offset:4096
	s_waitcnt lgkmcnt(4)
	v_mfma_f32_32x32x16_bf16 v[82:97], v[186:189], v[194:197], v[82:97]
	v_mfma_f32_32x32x16_bf16 v[18:33], v[190:193], v[194:197], v[18:33]
	ds_read_b128 v[194:197], v238 offset:20480
	s_waitcnt lgkmcnt(4)
	v_mfma_f32_32x32x16_bf16 v[66:81], v[186:189], v[198:201], v[66:81]
	v_mfma_f32_32x32x16_bf16 v[2:17], v[190:193], v[198:201], v[2:17]
	ds_read_b128 v[198:201], v238 offset:24576
	s_waitcnt lgkmcnt(2)
	v_mfma_f32_32x32x16_bf16 v[114:129], v[178:181], v[228:231], v[114:129]
	v_mfma_f32_32x32x16_bf16 v[50:65], v[182:185], v[228:231], v[50:65]
	ds_read_b128 v[228:231], v238 offset:28672
	ds_read_b128 v[186:189], v226
	s_waitcnt lgkmcnt(3)
	v_mfma_f32_32x32x16_bf16 v[98:113], v[178:181], v[194:197], v[98:113]
	v_mfma_f32_32x32x16_bf16 v[34:49], v[182:185], v[194:197], v[34:49]
	ds_read_b128 v[194:197], v239 offset:16384
	ds_read_b128 v[190:193], v226 offset:4096
	s_waitcnt lgkmcnt(4)
	v_mfma_f32_32x32x16_bf16 v[82:97], v[178:181], v[198:201], v[82:97]
	v_mfma_f32_32x32x16_bf16 v[18:33], v[182:185], v[198:201], v[18:33]
	ds_read_b128 v[198:201], v239 offset:20480
	s_waitcnt lgkmcnt(4)
	v_mfma_f32_32x32x16_bf16 v[66:81], v[178:181], v[228:231], v[66:81]
	v_mfma_f32_32x32x16_bf16 v[2:17], v[182:185], v[228:231], v[2:17]
	ds_read_b128 v[228:231], v239 offset:24576
	s_waitcnt lgkmcnt(2)
	v_mfma_f32_32x32x16_bf16 v[114:129], v[186:189], v[194:197], v[114:129]
	v_mfma_f32_32x32x16_bf16 v[50:65], v[190:193], v[194:197], v[50:65]
	ds_read_b128 v[194:197], v239 offset:28672
	s_waitcnt lgkmcnt(2)
	v_mfma_f32_32x32x16_bf16 v[98:113], v[186:189], v[198:201], v[98:113]
	v_mfma_f32_32x32x16_bf16 v[34:49], v[190:193], v[198:201], v[34:49]
	s_waitcnt lgkmcnt(1)
	v_mfma_f32_32x32x16_bf16 v[82:97], v[186:189], v[228:231], v[82:97]
	v_mfma_f32_32x32x16_bf16 v[18:33], v[190:193], v[228:231], v[18:33]
	s_waitcnt lgkmcnt(0)
	v_mfma_f32_32x32x16_bf16 v[66:81], v[186:189], v[194:197], v[66:81]
	v_mfma_f32_32x32x16_bf16 v[2:17], v[190:193], v[194:197], v[2:17]
	s_setprio 0
	s_barrier
	s_mov_b64 s[2:3], -1
	s_mov_b64 vcc, 0
	s_branch .LBB0_893

.Lg3_head:
	s_cmpk_gt_u32 s21, 0x7bf
	s_waitcnt vmcnt(0)
	ds_write_b128 v222, v[134:137]
	ds_write_b128 v222, v[130:133] offset:4096
	ds_write_b128 v222, v[142:145] offset:8192
	ds_write_b128 v222, v[138:141] offset:12288
	ds_write_b128 v222, v[146:149] offset:16384
	ds_write_b128 v222, v[150:153] offset:20480
	ds_write_b128 v222, v[154:157] offset:24576
	ds_write_b128 v222, v[158:161] offset:28672
	ds_write_b128 v222, v[162:165] offset:32768
	ds_write_b128 v222, v[166:169] offset:36864
	ds_write_b128 v222, v[170:173] offset:40960
	ds_write_b128 v222, v[174:177] offset:45056
	s_waitcnt lgkmcnt(0)
	s_barrier
	s_cbranch_scc1 .Lg3_final
	s_add_i32 s21, s21, 64
	s_setprio 1
	ds_read_b128 v[178:181], v224
	ds_read_b128 v[182:185], v224 offset:4096
	ds_read_b128 v[194:197], v235 offset:16384
	ds_read_b128 v[198:201], v235 offset:20480
	ds_read_b128 v[210:213], v235 offset:24576
	s_waitcnt lgkmcnt(2)
	v_mfma_f32_32x32x16_bf16 v[114:129], v[178:181], v[194:197], v[114:129]
	v_mfma_f32_32x32x16_bf16 v[50:65], v[182:185], v[194:197], v[50:65]
	ds_read_b128 v[194:197], v235 offset:28672
	ds_read_b128 v[186:189], v226
	s_and_b64 exec, vcc, s[4:5]
	global_load_dwordx4 v[134:137], v202, s[26:27]
	s_mov_b64 exec, vcc
	s_waitcnt lgkmcnt(3)
	v_mfma_f32_32x32x16_bf16 v[98:113], v[178:181], v[198:201], v[98:113]
	v_mfma_f32_32x32x16_bf16 v[34:49], v[182:185], v[198:201], v[34:49]
	ds_read_b128 v[198:201], v236 offset:16384
	ds_read_b128 v[190:193], v226 offset:4096
	s_and_b64 exec, vcc, s[6:7]
	global_load_dwordx4 v[130:133], v203, s[26:27]
	s_mov_b64 exec, vcc
	s_waitcnt lgkmcnt(4)
	v_mfma_f32_32x32x16_bf16 v[82:97], v[178:181], v[210:213], v[82:97]
	v_mfma_f32_32x32x16_bf16 v[18:33], v[182:185], v[210:213], v[18:33]
	ds_read_b128 v[210:213], v236 offset:20480
	s_and_b64 exec, vcc, s[8:9]
	global_load_dwordx4 v[142:145], v230, s[26:27]
	s_mov_b64 exec, vcc
	s_waitcnt lgkmcnt(4)
	v_mfma_f32_32x32x16_bf16 v[66:81], v[178:181], v[194:197], v[66:81]
	v_mfma_f32_32x32x16_bf16 v[2:17], v[182:185], v[194:197], v[2:17]
	ds_read_b128 v[194:197], v236 offset:24576
	s_and_b64 exec, vcc, s[10:11]
	global_load_dwordx4 v[138:141], v231, s[26:27]
	s_mov_b64 exec, vcc
	s_add_u32 s26, s26, 0x80
	s_addc_u32 s27, s27, 0
	s_waitcnt lgkmcnt(2)
	v_mfma_f32_32x32x16_bf16 v[114:129], v[186:189], v[198:201], v[114:129]
	v_mfma_f32_32x32x16_bf16 v[50:65], v[190:193], v[198:201], v[50:65]
	ds_read_b128 v[198:201], v236 offset:28672
	ds_read_b128 v[178:181], v228
	global_load_dwordx4 v[146:149], v232, s[100:101]
	s_waitcnt lgkmcnt(3)
	v_mfma_f32_32x32x16_bf16 v[98:113], v[186:189], v[210:213], v[98:113]
	v_mfma_f32_32x32x16_bf16 v[34:49], v[190:193], v[210:213], v[34:49]
	ds_read_b128 v[210:213], v237 offset:16384
	ds_read_b128 v[182:185], v228 offset:4096
	v_add_u32_e32 v233, 0x20000, v232
	global_load_dwordx4 v[150:153], v233, s[100:101]
	s_waitcnt lgkmcnt(4)
	v_mfma_f32_32x32x16_bf16 v[82:97], v[186:189], v[194:197], v[82:97]
	v_mfma_f32_32x32x16_bf16 v[18:33], v[190:193], v[194:197], v[18:33]
	ds_read_b128 v[194:197], v237 offset:20480
	v_add_u32_e32 v234, 0x40000, v232
	global_load_dwordx4 v[154:157], v234, s[100:101]
	s_waitcnt lgkmcnt(4)
	v_mfma_f32_32x32x16_bf16 v[66:81], v[186:189], v[198:201], v[66:81]
	v_mfma_f32_32x32x16_bf16 v[2:17], v[190:193], v[198:201], v[2:17]
	ds_read_b128 v[198:201], v237 offset:24576
	v_add_u32_e32 v233, 0x60000, v232
	global_load_dwordx4 v[158:161], v233, s[100:101]
	s_waitcnt lgkmcnt(2)
	v_mfma_f32_32x32x16_bf16 v[114:129], v[178:181], v[210:213], v[114:129]
	v_mfma_f32_32x32x16_bf16 v[50:65], v[182:185], v[210:213], v[50:65]
	ds_read_b128 v[210:213], v237 offset:28672
	ds_read_b128 v[186:189], v229
	v_add_u32_e32 v234, 0x80000, v232
	global_load_dwordx4 v[162:165], v234, s[100:101]
	s_waitcnt lgkmcnt(3)
	v_mfma_f32_32x32x16_bf16 v[98:113], v[178:181], v[194:197], v[98:113]
	v_mfma_f32_32x32x16_bf16 v[34:49], v[182:185], v[194:197], v[34:49]
	ds_read_b128 v[194:197], v238 offset:16384
	ds_read_b128 v[190:193], v229 offset:4096
	v_add_u32_e32 v233, 0xa0000, v232
	global_load_dwordx4 v[166:169], v233, s[100:101]
	s_waitcnt lgkmcnt(4)
	v_mfma_f32_32x32x16_bf16 v[82:97], v[178:181], v[198:201], v[82:97]
	v_mfma_f32_32x32x16_bf16 v[18:33], v[182:185], v[198:201], v[18:33]
	ds_read_b128 v[198:201], v238 offset:20480
	v_add_u32_e32 v234, 0xc0000, v232
	global_load_dwordx4 v[170:173], v234, s[100:101]
	s_waitcnt lgkmcnt(4)
	v_mfma_f32_32x32x16_bf16 v[66:81], v[178:181], v[210:213], v[66:81]
	v_mfma_f32_32x32x16_bf16 v[2:17], v[182:185], v[210:213], v[2:17]
	ds_read_b128 v[210:213], v238 offset:24576
	v_add_u32_e32 v233, 0xe0000, v232
	global_load_dwordx4 v[174:177], v233, s[100:101]
	s_add_u32 s100, s100, 0x80
	s_addc_u32 s101, s101, 0
	s_waitcnt lgkmcnt(2)
	v_mfma_f32_32x32x16_bf16 v[114:129], v[186:189], v[194:197], v[114:129]
	v_mfma_f32_32x32x16_bf16 v[50:65], v[190:193], v[194:197], v[50:65]
	ds_read_b128 v[194:197], v238 offset:28672
	s_waitcnt lgkmcnt(2)
	v_mfma_f32_32x32x16_bf16 v[98:113], v[186:189], v[198:201], v[98:113]
	v_mfma_f32_32x32x16_bf16 v[34:49], v[190:193], v[198:201], v[34:49]
	s_waitcnt lgkmcnt(1)
	v_mfma_f32_32x32x16_bf16 v[82:97], v[186:189], v[210:213], v[82:97]
	v_mfma_f32_32x32x16_bf16 v[18:33], v[190:193], v[210:213], v[18:33]
	s_waitcnt lgkmcnt(0)
	v_mfma_f32_32x32x16_bf16 v[66:81], v[186:189], v[194:197], v[66:81]
	v_mfma_f32_32x32x16_bf16 v[2:17], v[190:193], v[194:197], v[2:17]
	s_setprio 0
	s_barrier
	s_branch .Lg3_head
.Lg3_final:
	s_add_i32 s21, s21, 64
	s_setprio 1
	ds_read_b128 v[178:181], v224
	ds_read_b128 v[182:185], v224 offset:4096
	ds_read_b128 v[194:197], v235 offset:16384
	ds_read_b128 v[198:201], v235 offset:20480
	ds_read_b128 v[210:213], v235 offset:24576
	s_waitcnt lgkmcnt(2)
	v_mfma_f32_32x32x16_bf16 v[114:129], v[178:181], v[194:197], v[114:129]
	v_mfma_f32_32x32x16_bf16 v[50:65], v[182:185], v[194:197], v[50:65]
	ds_read_b128 v[194:197], v235 offset:28672
	ds_read_b128 v[186:189], v226
	s_waitcnt lgkmcnt(3)
	v_mfma_f32_32x32x16_bf16 v[98:113], v[178:181], v[198:201], v[98:113]
	v_mfma_f32_32x32x16_bf16 v[34:49], v[182:185], v[198:201], v[34:49]
	ds_read_b128 v[198:201], v236 offset:16384
	ds_read_b128 v[190:193], v226 offset:4096
	s_waitcnt lgkmcnt(4)
	v_mfma_f32_32x32x16_bf16 v[82:97], v[178:181], v[210:213], v[82:97]
	v_mfma_f32_32x32x16_bf16 v[18:33], v[182:185], v[210:213], v[18:33]
	ds_read_b128 v[210:213], v236 offset:20480
	s_waitcnt lgkmcnt(4)
	v_mfma_f32_32x32x16_bf16 v[66:81], v[178:181], v[194:197], v[66:81]
	v_mfma_f32_32x32x16_bf16 v[2:17], v[182:185], v[194:197], v[2:17]
	ds_read_b128 v[194:197], v236 offset:24576
	s_waitcnt lgkmcnt(2)
	v_mfma_f32_32x32x16_bf16 v[114:129], v[186:189], v[198:201], v[114:129]
	v_mfma_f32_32x32x16_bf16 v[50:65], v[190:193], v[198:201], v[50:65]
	ds_read_b128 v[198:201], v236 offset:28672
	ds_read_b128 v[178:181], v228
	s_waitcnt lgkmcnt(3)
	v_mfma_f32_32x32x16_bf16 v[98:113], v[186:189], v[210:213], v[98:113]
	v_mfma_f32_32x32x16_bf16 v[34:49], v[190:193], v[210:213], v[34:49]
	ds_read_b128 v[210:213], v237 offset:16384
	ds_read_b128 v[182:185], v228 offset:4096
	s_waitcnt lgkmcnt(4)
	v_mfma_f32_32x32x16_bf16 v[82:97], v[186:189], v[194:197], v[82:97]
	v_mfma_f32_32x32x16_bf16 v[18:33], v[190:193], v[194:197], v[18:33]
	ds_read_b128 v[194:197], v237 offset:20480
	s_waitcnt lgkmcnt(4)
	v_mfma_f32_32x32x16_bf16 v[66:81], v[186:189], v[198:201], v[66:81]
	v_mfma_f32_32x32x16_bf16 v[2:17], v[190:193], v[198:201], v[2:17]
	ds_read_b128 v[198:201], v237 offset:24576
	s_waitcnt lgkmcnt(2)
	v_mfma_f32_32x32x16_bf16 v[114:129], v[178:181], v[210:213], v[114:129]
	v_mfma_f32_32x32x16_bf16 v[50:65], v[182:185], v[210:213], v[50:65]
	ds_read_b128 v[210:213], v237 offset:28672
	ds_read_b128 v[186:189], v229
	s_waitcnt lgkmcnt(3)
	v_mfma_f32_32x32x16_bf16 v[98:113], v[178:181], v[194:197], v[98:113]
	v_mfma_f32_32x32x16_bf16 v[34:49], v[182:185], v[194:197], v[34:49]
	ds_read_b128 v[194:197], v238 offset:16384
	ds_read_b128 v[190:193], v229 offset:4096
	s_waitcnt lgkmcnt(4)
	v_mfma_f32_32x32x16_bf16 v[82:97], v[178:181], v[198:201], v[82:97]
	v_mfma_f32_32x32x16_bf16 v[18:33], v[182:185], v[198:201], v[18:33]
	ds_read_b128 v[198:201], v238 offset:20480
	s_waitcnt lgkmcnt(4)
	v_mfma_f32_32x32x16_bf16 v[66:81], v[178:181], v[210:213], v[66:81]
	v_mfma_f32_32x32x16_bf16 v[2:17], v[182:185], v[210:213], v[2:17]
	ds_read_b128 v[210:213], v238 offset:24576
	s_waitcnt lgkmcnt(2)
	v_mfma_f32_32x32x16_bf16 v[114:129], v[186:189], v[194:197], v[114:129]
	v_mfma_f32_32x32x16_bf16 v[50:65], v[190:193], v[194:197], v[50:65]
	ds_read_b128 v[194:197], v238 offset:28672
	s_waitcnt lgkmcnt(2)
	v_mfma_f32_32x32x16_bf16 v[98:113], v[186:189], v[198:201], v[98:113]
	v_mfma_f32_32x32x16_bf16 v[34:49], v[190:193], v[198:201], v[34:49]
	s_waitcnt lgkmcnt(1)
	v_mfma_f32_32x32x16_bf16 v[82:97], v[186:189], v[210:213], v[82:97]
	v_mfma_f32_32x32x16_bf16 v[18:33], v[190:193], v[210:213], v[18:33]
	s_waitcnt lgkmcnt(0)
	v_mfma_f32_32x32x16_bf16 v[66:81], v[186:189], v[194:197], v[66:81]
	v_mfma_f32_32x32x16_bf16 v[2:17], v[190:193], v[194:197], v[2:17]
	s_setprio 0
	s_barrier
	s_mov_b64 s[22:23], -1
	s_mov_b64 vcc, 0
	s_branch .LBB0_1966

.Lg4_head:
	s_cmpk_gt_u32 s39, 0x7bf
	s_waitcnt vmcnt(0)
	ds_write_b128 v224, v[134:137]
	ds_write_b128 v224, v[130:133] offset:4096
	ds_write_b128 v224, v[142:145] offset:8192
	ds_write_b128 v224, v[138:141] offset:12288
	ds_write_b128 v224, v[146:149] offset:16384
	ds_write_b128 v224, v[150:153] offset:20480
	ds_write_b128 v224, v[154:157] offset:24576
	ds_write_b128 v224, v[158:161] offset:28672
	ds_write_b128 v224, v[162:165] offset:32768
	ds_write_b128 v224, v[166:169] offset:36864
	ds_write_b128 v224, v[170:173] offset:40960
	ds_write_b128 v224, v[174:177] offset:45056
	s_waitcnt lgkmcnt(0)
	s_barrier
	s_cbranch_scc1 .Lg4_final
	s_add_i32 s39, s39, 64
	s_setprio 1
	ds_read_b128 v[180:183], v226
	ds_read_b128 v[184:187], v226 offset:4096
	ds_read_b128 v[196:199], v237 offset:16384
	ds_read_b128 v[200:203], v237 offset:20480
	ds_read_b128 v[210:213], v237 offset:24576
	s_waitcnt lgkmcnt(2)
	v_mfma_f32_32x32x16_bf16 v[114:129], v[180:183], v[196:199], v[114:129]
	v_mfma_f32_32x32x16_bf16 v[50:65], v[184:187], v[196:199], v[50:65]
	ds_read_b128 v[196:199], v237 offset:28672
	ds_read_b128 v[188:191], v228
	s_and_b64 exec, vcc, s[14:15]
	global_load_dwordx4 v[134:137], v204, s[22:23]
	s_mov_b64 exec, vcc
	s_waitcnt lgkmcnt(3)
	v_mfma_f32_32x32x16_bf16 v[98:113], v[180:183], v[200:203], v[98:113]
	v_mfma_f32_32x32x16_bf16 v[34:49], v[184:187], v[200:203], v[34:49]
	ds_read_b128 v[200:203], v238 offset:16384
	ds_read_b128 v[192:195], v228 offset:4096
	s_and_b64 exec, vcc, s[16:17]
	global_load_dwordx4 v[130:133], v205, s[22:23]
	s_mov_b64 exec, vcc
	s_waitcnt lgkmcnt(4)
	v_mfma_f32_32x32x16_bf16 v[82:97], v[180:183], v[210:213], v[82:97]
	v_mfma_f32_32x32x16_bf16 v[18:33], v[184:187], v[210:213], v[18:33]
	ds_read_b128 v[210:213], v238 offset:20480
	s_and_b64 exec, vcc, s[18:19]
	global_load_dwordx4 v[142:145], v232, s[22:23]
	s_mov_b64 exec, vcc
	s_waitcnt lgkmcnt(4)
	v_mfma_f32_32x32x16_bf16 v[66:81], v[180:183], v[196:199], v[66:81]
	v_mfma_f32_32x32x16_bf16 v[2:17], v[184:187], v[196:199], v[2:17]
	ds_read_b128 v[196:199], v238 offset:24576
	s_and_b64 exec, vcc, s[4:5]
	global_load_dwordx4 v[138:141], v233, s[22:23]
	s_mov_b64 exec, vcc
	s_add_u32 s22, s22, 0x80
	s_addc_u32 s23, s23, 0
	s_waitcnt lgkmcnt(2)
	v_mfma_f32_32x32x16_bf16 v[114:129], v[188:191], v[200:203], v[114:129]
	v_mfma_f32_32x32x16_bf16 v[50:65], v[192:195], v[200:203], v[50:65]
	ds_read_b128 v[200:203], v238 offset:28672
	ds_read_b128 v[180:183], v230
	global_load_dwordx4 v[146:149], v234, s[100:101]
	s_waitcnt lgkmcnt(3)
	v_mfma_f32_32x32x16_bf16 v[98:113], v[188:191], v[210:213], v[98:113]
	v_mfma_f32_32x32x16_bf16 v[34:49], v[192:195], v[210:213], v[34:49]
	ds_read_b128 v[210:213], v239 offset:16384
	ds_read_b128 v[184:187], v230 offset:4096
	v_add_u32_e32 v235, 0x20000, v234
	global_load_dwordx4 v[150:153], v235, s[100:101]
	s_waitcnt lgkmcnt(4)
	v_mfma_f32_32x32x16_bf16 v[82:97], v[188:191], v[196:199], v[82:97]
	v_mfma_f32_32x32x16_bf16 v[18:33], v[192:195], v[196:199], v[18:33]
	ds_read_b128 v[196:199], v239 offset:20480
	v_add_u32_e32 v236, 0x40000, v234
	global_load_dwordx4 v[154:157], v236, s[100:101]
	s_waitcnt lgkmcnt(4)
	v_mfma_f32_32x32x16_bf16 v[66:81], v[188:191], v[200:203], v[66:81]
	v_mfma_f32_32x32x16_bf16 v[2:17], v[192:195], v[200:203], v[2:17]
	ds_read_b128 v[200:203], v239 offset:24576
	v_add_u32_e32 v235, 0x60000, v234
	global_load_dwordx4 v[158:161], v235, s[100:101]
	s_waitcnt lgkmcnt(2)
	v_mfma_f32_32x32x16_bf16 v[114:129], v[180:183], v[210:213], v[114:129]
	v_mfma_f32_32x32x16_bf16 v[50:65], v[184:187], v[210:213], v[50:65]
	ds_read_b128 v[210:213], v239 offset:28672
	ds_read_b128 v[188:191], v231
	v_add_u32_e32 v236, 0x80000, v234
	global_load_dwordx4 v[162:165], v236, s[100:101]
	s_waitcnt lgkmcnt(3)
	v_mfma_f32_32x32x16_bf16 v[98:113], v[180:183], v[196:199], v[98:113]
	v_mfma_f32_32x32x16_bf16 v[34:49], v[184:187], v[196:199], v[34:49]
	ds_read_b128 v[196:199], v240 offset:16384
	ds_read_b128 v[192:195], v231 offset:4096
	v_add_u32_e32 v235, 0xa0000, v234
	global_load_dwordx4 v[166:169], v235, s[100:101]
	s_waitcnt lgkmcnt(4)
	v_mfma_f32_32x32x16_bf16 v[82:97], v[180:183], v[200:203], v[82:97]
	v_mfma_f32_32x32x16_bf16 v[18:33], v[184:187], v[200:203], v[18:33]
	ds_read_b128 v[200:203], v240 offset:20480
	v_add_u32_e32 v236, 0xc0000, v234
	global_load_dwordx4 v[170:173], v236, s[100:101]
	s_waitcnt lgkmcnt(4)
	v_mfma_f32_32x32x16_bf16 v[66:81], v[180:183], v[210:213], v[66:81]
	v_mfma_f32_32x32x16_bf16 v[2:17], v[184:187], v[210:213], v[2:17]
	ds_read_b128 v[210:213], v240 offset:24576
	v_add_u32_e32 v235, 0xe0000, v234
	global_load_dwordx4 v[174:177], v235, s[100:101]
	s_add_u32 s100, s100, 0x80
	s_addc_u32 s101, s101, 0
	s_waitcnt lgkmcnt(2)
	v_mfma_f32_32x32x16_bf16 v[114:129], v[188:191], v[196:199], v[114:129]
	v_mfma_f32_32x32x16_bf16 v[50:65], v[192:195], v[196:199], v[50:65]
	ds_read_b128 v[196:199], v240 offset:28672
	s_waitcnt lgkmcnt(2)
	v_mfma_f32_32x32x16_bf16 v[98:113], v[188:191], v[200:203], v[98:113]
	v_mfma_f32_32x32x16_bf16 v[34:49], v[192:195], v[200:203], v[34:49]
	s_waitcnt lgkmcnt(1)
	v_mfma_f32_32x32x16_bf16 v[82:97], v[188:191], v[210:213], v[82:97]
	v_mfma_f32_32x32x16_bf16 v[18:33], v[192:195], v[210:213], v[18:33]
	s_waitcnt lgkmcnt(0)
	v_mfma_f32_32x32x16_bf16 v[66:81], v[188:191], v[196:199], v[66:81]
	v_mfma_f32_32x32x16_bf16 v[2:17], v[192:195], v[196:199], v[2:17]
	s_setprio 0
	s_barrier
	s_branch .Lg4_head
.Lg4_final:
	s_add_i32 s39, s39, 64
	s_setprio 1
	ds_read_b128 v[180:183], v226
	ds_read_b128 v[184:187], v226 offset:4096
	ds_read_b128 v[196:199], v237 offset:16384
	ds_read_b128 v[200:203], v237 offset:20480
	ds_read_b128 v[210:213], v237 offset:24576
	s_waitcnt lgkmcnt(2)
	v_mfma_f32_32x32x16_bf16 v[114:129], v[180:183], v[196:199], v[114:129]
	v_mfma_f32_32x32x16_bf16 v[50:65], v[184:187], v[196:199], v[50:65]
	ds_read_b128 v[196:199], v237 offset:28672
	ds_read_b128 v[188:191], v228
	s_waitcnt lgkmcnt(3)
	v_mfma_f32_32x32x16_bf16 v[98:113], v[180:183], v[200:203], v[98:113]
	v_mfma_f32_32x32x16_bf16 v[34:49], v[184:187], v[200:203], v[34:49]
	ds_read_b128 v[200:203], v238 offset:16384
	ds_read_b128 v[192:195], v228 offset:4096
	s_waitcnt lgkmcnt(4)
	v_mfma_f32_32x32x16_bf16 v[82:97], v[180:183], v[210:213], v[82:97]
	v_mfma_f32_32x32x16_bf16 v[18:33], v[184:187], v[210:213], v[18:33]
	ds_read_b128 v[210:213], v238 offset:20480
	s_waitcnt lgkmcnt(4)
	v_mfma_f32_32x32x16_bf16 v[66:81], v[180:183], v[196:199], v[66:81]
	v_mfma_f32_32x32x16_bf16 v[2:17], v[184:187], v[196:199], v[2:17]
	ds_read_b128 v[196:199], v238 offset:24576
	s_waitcnt lgkmcnt(2)
	v_mfma_f32_32x32x16_bf16 v[114:129], v[188:191], v[200:203], v[114:129]
	v_mfma_f32_32x32x16_bf16 v[50:65], v[192:195], v[200:203], v[50:65]
	ds_read_b128 v[200:203], v238 offset:28672
	ds_read_b128 v[180:183], v230
	s_waitcnt lgkmcnt(3)
	v_mfma_f32_32x32x16_bf16 v[98:113], v[188:191], v[210:213], v[98:113]
	v_mfma_f32_32x32x16_bf16 v[34:49], v[192:195], v[210:213], v[34:49]
	ds_read_b128 v[210:213], v239 offset:16384
	ds_read_b128 v[184:187], v230 offset:4096
	s_waitcnt lgkmcnt(4)
	v_mfma_f32_32x32x16_bf16 v[82:97], v[188:191], v[196:199], v[82:97]
	v_mfma_f32_32x32x16_bf16 v[18:33], v[192:195], v[196:199], v[18:33]
	ds_read_b128 v[196:199], v239 offset:20480
	s_waitcnt lgkmcnt(4)
	v_mfma_f32_32x32x16_bf16 v[66:81], v[188:191], v[200:203], v[66:81]
	v_mfma_f32_32x32x16_bf16 v[2:17], v[192:195], v[200:203], v[2:17]
	ds_read_b128 v[200:203], v239 offset:24576
	s_waitcnt lgkmcnt(2)
	v_mfma_f32_32x32x16_bf16 v[114:129], v[180:183], v[210:213], v[114:129]
	v_mfma_f32_32x32x16_bf16 v[50:65], v[184:187], v[210:213], v[50:65]
	ds_read_b128 v[210:213], v239 offset:28672
	ds_read_b128 v[188:191], v231
	s_waitcnt lgkmcnt(3)
	v_mfma_f32_32x32x16_bf16 v[98:113], v[180:183], v[196:199], v[98:113]
	v_mfma_f32_32x32x16_bf16 v[34:49], v[184:187], v[196:199], v[34:49]
	ds_read_b128 v[196:199], v240 offset:16384
	ds_read_b128 v[192:195], v231 offset:4096
	s_waitcnt lgkmcnt(4)
	v_mfma_f32_32x32x16_bf16 v[82:97], v[180:183], v[200:203], v[82:97]
	v_mfma_f32_32x32x16_bf16 v[18:33], v[184:187], v[200:203], v[18:33]
	ds_read_b128 v[200:203], v240 offset:20480
	s_waitcnt lgkmcnt(4)
	v_mfma_f32_32x32x16_bf16 v[66:81], v[180:183], v[210:213], v[66:81]
	v_mfma_f32_32x32x16_bf16 v[2:17], v[184:187], v[210:213], v[2:17]
	ds_read_b128 v[210:213], v240 offset:24576
	s_waitcnt lgkmcnt(2)
	v_mfma_f32_32x32x16_bf16 v[114:129], v[188:191], v[196:199], v[114:129]
	v_mfma_f32_32x32x16_bf16 v[50:65], v[192:195], v[196:199], v[50:65]
	ds_read_b128 v[196:199], v240 offset:28672
	s_waitcnt lgkmcnt(2)
	v_mfma_f32_32x32x16_bf16 v[98:113], v[188:191], v[200:203], v[98:113]
	v_mfma_f32_32x32x16_bf16 v[34:49], v[192:195], v[200:203], v[34:49]
	s_waitcnt lgkmcnt(1)
	v_mfma_f32_32x32x16_bf16 v[82:97], v[188:191], v[210:213], v[82:97]
	v_mfma_f32_32x32x16_bf16 v[18:33], v[192:195], v[210:213], v[18:33]
	s_waitcnt lgkmcnt(0)
	v_mfma_f32_32x32x16_bf16 v[66:81], v[188:191], v[196:199], v[66:81]
	v_mfma_f32_32x32x16_bf16 v[2:17], v[192:195], v[196:199], v[2:17]
	s_setprio 0
	s_barrier
	s_mov_b64 s[20:21], -1
	s_mov_b64 vcc, 0
	s_branch .LBB0_2103

.Lg5_head:
	s_cmpk_gt_u32 s17, 0xfbf
	s_waitcnt vmcnt(0)
	ds_write_b128 v222, v[134:137]
	ds_write_b128 v222, v[130:133] offset:4096
	ds_write_b128 v222, v[142:145] offset:8192
	ds_write_b128 v222, v[138:141] offset:12288
	ds_write_b128 v222, v[146:149] offset:16384
	ds_write_b128 v222, v[150:153] offset:20480
	ds_write_b128 v222, v[154:157] offset:24576
	ds_write_b128 v222, v[158:161] offset:28672
	ds_write_b128 v222, v[162:165] offset:32768
	ds_write_b128 v222, v[166:169] offset:36864
	ds_write_b128 v222, v[170:173] offset:40960
	ds_write_b128 v222, v[174:177] offset:45056
	s_waitcnt lgkmcnt(0)
	s_barrier
	s_cbranch_scc1 .Lg5_final
	s_add_i32 s17, s17, 64
	s_setprio 1
	ds_read_b128 v[178:181], v224
	ds_read_b128 v[182:185], v224 offset:4096
	ds_read_b128 v[194:197], v235 offset:16384
	ds_read_b128 v[198:201], v235 offset:20480
	ds_read_b128 v[210:213], v235 offset:24576
	s_waitcnt lgkmcnt(2)
	v_mfma_f32_32x32x16_bf16 v[114:129], v[178:181], v[194:197], v[114:129]
	v_mfma_f32_32x32x16_bf16 v[50:65], v[182:185], v[194:197], v[50:65]
	ds_read_b128 v[194:197], v235 offset:28672
	ds_read_b128 v[186:189], v226
	s_and_b64 exec, vcc, s[2:3]
	global_load_dwordx4 v[134:137], v202, s[20:21]
	s_mov_b64 exec, vcc
	s_waitcnt lgkmcnt(3)
	v_mfma_f32_32x32x16_bf16 v[98:113], v[178:181], v[198:201], v[98:113]
	v_mfma_f32_32x32x16_bf16 v[34:49], v[182:185], v[198:201], v[34:49]
	ds_read_b128 v[198:201], v236 offset:16384
	ds_read_b128 v[190:193], v226 offset:4096
	s_and_b64 exec, vcc, s[4:5]
	global_load_dwordx4 v[130:133], v203, s[20:21]
	s_mov_b64 exec, vcc
	s_waitcnt lgkmcnt(4)
	v_mfma_f32_32x32x16_bf16 v[82:97], v[178:181], v[210:213], v[82:97]
	v_mfma_f32_32x32x16_bf16 v[18:33], v[182:185], v[210:213], v[18:33]
	ds_read_b128 v[210:213], v236 offset:20480
	s_and_b64 exec, vcc, s[6:7]
	global_load_dwordx4 v[142:145], v230, s[20:21]
	s_mov_b64 exec, vcc
	s_waitcnt lgkmcnt(4)
	v_mfma_f32_32x32x16_bf16 v[66:81], v[178:181], v[194:197], v[66:81]
	v_mfma_f32_32x32x16_bf16 v[2:17], v[182:185], v[194:197], v[2:17]
	ds_read_b128 v[194:197], v236 offset:24576
	s_and_b64 exec, vcc, s[8:9]
	global_load_dwordx4 v[138:141], v231, s[20:21]
	s_mov_b64 exec, vcc
	s_add_u32 s20, s20, 0x80
	s_addc_u32 s21, s21, 0
	s_waitcnt lgkmcnt(2)
	v_mfma_f32_32x32x16_bf16 v[114:129], v[186:189], v[198:201], v[114:129]
	v_mfma_f32_32x32x16_bf16 v[50:65], v[190:193], v[198:201], v[50:65]
	ds_read_b128 v[198:201], v236 offset:28672
	ds_read_b128 v[178:181], v228
	global_load_dwordx4 v[146:149], v232, s[100:101]
	s_waitcnt lgkmcnt(3)
	v_mfma_f32_32x32x16_bf16 v[98:113], v[186:189], v[210:213], v[98:113]
	v_mfma_f32_32x32x16_bf16 v[34:49], v[190:193], v[210:213], v[34:49]
	ds_read_b128 v[210:213], v237 offset:16384
	ds_read_b128 v[182:185], v228 offset:4096
	v_add_u32_e32 v233, 0x40000, v232
	global_load_dwordx4 v[150:153], v233, s[100:101]
	s_waitcnt lgkmcnt(4)
	v_mfma_f32_32x32x16_bf16 v[82:97], v[186:189], v[194:197], v[82:97]
	v_mfma_f32_32x32x16_bf16 v[18:33], v[190:193], v[194:197], v[18:33]
	ds_read_b128 v[194:197], v237 offset:20480
	v_add_u32_e32 v234, 0x80000, v232
	global_load_dwordx4 v[154:157], v234, s[100:101]
	s_waitcnt lgkmcnt(4)
	v_mfma_f32_32x32x16_bf16 v[66:81], v[186:189], v[198:201], v[66:81]
	v_mfma_f32_32x32x16_bf16 v[2:17], v[190:193], v[198:201], v[2:17]
	ds_read_b128 v[198:201], v237 offset:24576
	v_add_u32_e32 v233, 0xc0000, v232
	global_load_dwordx4 v[158:161], v233, s[100:101]
	s_waitcnt lgkmcnt(2)
	v_mfma_f32_32x32x16_bf16 v[114:129], v[178:181], v[210:213], v[114:129]
	v_mfma_f32_32x32x16_bf16 v[50:65], v[182:185], v[210:213], v[50:65]
	ds_read_b128 v[210:213], v237 offset:28672
	ds_read_b128 v[186:189], v229
	v_add_u32_e32 v234, 0x100000, v232
	global_load_dwordx4 v[162:165], v234, s[100:101]
	s_waitcnt lgkmcnt(3)
	v_mfma_f32_32x32x16_bf16 v[98:113], v[178:181], v[194:197], v[98:113]
	v_mfma_f32_32x32x16_bf16 v[34:49], v[182:185], v[194:197], v[34:49]
	ds_read_b128 v[194:197], v238 offset:16384
	ds_read_b128 v[190:193], v229 offset:4096
	v_add_u32_e32 v233, 0x140000, v232
	global_load_dwordx4 v[166:169], v233, s[100:101]
	s_waitcnt lgkmcnt(4)
	v_mfma_f32_32x32x16_bf16 v[82:97], v[178:181], v[198:201], v[82:97]
	v_mfma_f32_32x32x16_bf16 v[18:33], v[182:185], v[198:201], v[18:33]
	ds_read_b128 v[198:201], v238 offset:20480
	v_add_u32_e32 v234, 0x180000, v232
	global_load_dwordx4 v[170:173], v234, s[100:101]
	s_waitcnt lgkmcnt(4)
	v_mfma_f32_32x32x16_bf16 v[66:81], v[178:181], v[210:213], v[66:81]
	v_mfma_f32_32x32x16_bf16 v[2:17], v[182:185], v[210:213], v[2:17]
	ds_read_b128 v[210:213], v238 offset:24576
	v_add_u32_e32 v233, 0x1c0000, v232
	global_load_dwordx4 v[174:177], v233, s[100:101]
	s_add_u32 s100, s100, 0x80
	s_addc_u32 s101, s101, 0
	s_waitcnt lgkmcnt(2)
	v_mfma_f32_32x32x16_bf16 v[114:129], v[186:189], v[194:197], v[114:129]
	v_mfma_f32_32x32x16_bf16 v[50:65], v[190:193], v[194:197], v[50:65]
	ds_read_b128 v[194:197], v238 offset:28672
	s_waitcnt lgkmcnt(2)
	v_mfma_f32_32x32x16_bf16 v[98:113], v[186:189], v[198:201], v[98:113]
	v_mfma_f32_32x32x16_bf16 v[34:49], v[190:193], v[198:201], v[34:49]
	s_waitcnt lgkmcnt(1)
	v_mfma_f32_32x32x16_bf16 v[82:97], v[186:189], v[210:213], v[82:97]
	v_mfma_f32_32x32x16_bf16 v[18:33], v[190:193], v[210:213], v[18:33]
	s_waitcnt lgkmcnt(0)
	v_mfma_f32_32x32x16_bf16 v[66:81], v[186:189], v[194:197], v[66:81]
	v_mfma_f32_32x32x16_bf16 v[2:17], v[190:193], v[194:197], v[2:17]
	s_setprio 0
	s_barrier
	s_branch .Lg5_head
.Lg5_final:
	s_add_i32 s17, s17, 64
	s_setprio 1
	ds_read_b128 v[178:181], v224
	ds_read_b128 v[182:185], v224 offset:4096
	ds_read_b128 v[194:197], v235 offset:16384
	ds_read_b128 v[198:201], v235 offset:20480
	ds_read_b128 v[210:213], v235 offset:24576
	s_waitcnt lgkmcnt(2)
	v_mfma_f32_32x32x16_bf16 v[114:129], v[178:181], v[194:197], v[114:129]
	v_mfma_f32_32x32x16_bf16 v[50:65], v[182:185], v[194:197], v[50:65]
	ds_read_b128 v[194:197], v235 offset:28672
	ds_read_b128 v[186:189], v226
	s_waitcnt lgkmcnt(3)
	v_mfma_f32_32x32x16_bf16 v[98:113], v[178:181], v[198:201], v[98:113]
	v_mfma_f32_32x32x16_bf16 v[34:49], v[182:185], v[198:201], v[34:49]
	ds_read_b128 v[198:201], v236 offset:16384
	ds_read_b128 v[190:193], v226 offset:4096
	s_waitcnt lgkmcnt(4)
	v_mfma_f32_32x32x16_bf16 v[82:97], v[178:181], v[210:213], v[82:97]
	v_mfma_f32_32x32x16_bf16 v[18:33], v[182:185], v[210:213], v[18:33]
	ds_read_b128 v[210:213], v236 offset:20480
	s_waitcnt lgkmcnt(4)
	v_mfma_f32_32x32x16_bf16 v[66:81], v[178:181], v[194:197], v[66:81]
	v_mfma_f32_32x32x16_bf16 v[2:17], v[182:185], v[194:197], v[2:17]
	ds_read_b128 v[194:197], v236 offset:24576
	s_waitcnt lgkmcnt(2)
	v_mfma_f32_32x32x16_bf16 v[114:129], v[186:189], v[198:201], v[114:129]
	v_mfma_f32_32x32x16_bf16 v[50:65], v[190:193], v[198:201], v[50:65]
	ds_read_b128 v[198:201], v236 offset:28672
	ds_read_b128 v[178:181], v228
	s_waitcnt lgkmcnt(3)
	v_mfma_f32_32x32x16_bf16 v[98:113], v[186:189], v[210:213], v[98:113]
	v_mfma_f32_32x32x16_bf16 v[34:49], v[190:193], v[210:213], v[34:49]
	ds_read_b128 v[210:213], v237 offset:16384
	ds_read_b128 v[182:185], v228 offset:4096
	s_waitcnt lgkmcnt(4)
	v_mfma_f32_32x32x16_bf16 v[82:97], v[186:189], v[194:197], v[82:97]
	v_mfma_f32_32x32x16_bf16 v[18:33], v[190:193], v[194:197], v[18:33]
	ds_read_b128 v[194:197], v237 offset:20480
	s_waitcnt lgkmcnt(4)
	v_mfma_f32_32x32x16_bf16 v[66:81], v[186:189], v[198:201], v[66:81]
	v_mfma_f32_32x32x16_bf16 v[2:17], v[190:193], v[198:201], v[2:17]
	ds_read_b128 v[198:201], v237 offset:24576
	s_waitcnt lgkmcnt(2)
	v_mfma_f32_32x32x16_bf16 v[114:129], v[178:181], v[210:213], v[114:129]
	v_mfma_f32_32x32x16_bf16 v[50:65], v[182:185], v[210:213], v[50:65]
	ds_read_b128 v[210:213], v237 offset:28672
	ds_read_b128 v[186:189], v229
	s_waitcnt lgkmcnt(3)
	v_mfma_f32_32x32x16_bf16 v[98:113], v[178:181], v[194:197], v[98:113]
	v_mfma_f32_32x32x16_bf16 v[34:49], v[182:185], v[194:197], v[34:49]
	ds_read_b128 v[194:197], v238 offset:16384
	ds_read_b128 v[190:193], v229 offset:4096
	s_waitcnt lgkmcnt(4)
	v_mfma_f32_32x32x16_bf16 v[82:97], v[178:181], v[198:201], v[82:97]
	v_mfma_f32_32x32x16_bf16 v[18:33], v[182:185], v[198:201], v[18:33]
	ds_read_b128 v[198:201], v238 offset:20480
	s_waitcnt lgkmcnt(4)
	v_mfma_f32_32x32x16_bf16 v[66:81], v[178:181], v[210:213], v[66:81]
	v_mfma_f32_32x32x16_bf16 v[2:17], v[182:185], v[210:213], v[2:17]
	ds_read_b128 v[210:213], v238 offset:24576
	s_waitcnt lgkmcnt(2)
	v_mfma_f32_32x32x16_bf16 v[114:129], v[186:189], v[194:197], v[114:129]
	v_mfma_f32_32x32x16_bf16 v[50:65], v[190:193], v[194:197], v[50:65]
	ds_read_b128 v[194:197], v238 offset:28672
	s_waitcnt lgkmcnt(2)
	v_mfma_f32_32x32x16_bf16 v[98:113], v[186:189], v[198:201], v[98:113]
	v_mfma_f32_32x32x16_bf16 v[34:49], v[190:193], v[198:201], v[34:49]
	s_waitcnt lgkmcnt(1)
	v_mfma_f32_32x32x16_bf16 v[82:97], v[186:189], v[210:213], v[82:97]
	v_mfma_f32_32x32x16_bf16 v[18:33], v[190:193], v[210:213], v[18:33]
	s_waitcnt lgkmcnt(0)
	v_mfma_f32_32x32x16_bf16 v[66:81], v[186:189], v[194:197], v[66:81]
	v_mfma_f32_32x32x16_bf16 v[2:17], v[190:193], v[194:197], v[2:17]
	s_setprio 0
	s_barrier
	s_mov_b64 s[18:19], -1
	s_mov_b64 vcc, 0
	s_branch .LBB0_2186
